# scan loop heads: hipcc's materialised wave-uniform branch tests (9 SALU after the step barrier) reduced to one compare and branch
# speedup vs baseline: 1.0066x; 1.0065x over previous
; #define LAS __attribute__((address_space(3)))
; __device__ __forceinline__ unsigned pk2(float lo, float hi) { const f32x2_t v = {lo, hi}; const bf16x2_t b = __builtin_convertvector(v, bf16x2_t); return __builtin_bit_cast(unsigned, b); }
; __device__ __forceinline__ bf16x8 cat8(const s16x4 a, const s16x4 b) { return __builtin_shufflevector(a, b, 0, 1, 2, 3, 4, 5, 6, 7); }
; __device__ __forceinline__ void hgrn_scan(const Params& p, LAS unsigned char* lds, int chain) {
;     ...
;         bf16x8 vf[2];
; #pragma unroll
;         for (int sp = 0; sp < 2; ++sp) {
;             const LAS unsigned char* vb0 = bb + SB_V + (32 * sp + 4 * g + qq) * VP + (16 * wave + 4 * pp) * 2;
;             vf[sp] = cat8(lds_tr(vb0), lds_tr(vb0 + 16 * VP));
;         }
;         if (lat) {
;             bf16x8 sb[4];
; #pragma unroll
;             for (int ks = 0; ks < 4; ++ks) sb[ks] = pack_p(S[2 * ks], S[2 * ks + 1]);
;             bf16* orow = O + (long)hg_row(dir, b, 64 * c) * WA;
; #pragma unroll
;             for (int I = 0; I < 4; ++I) {
;                 f32x4 o = (f32x4){0.f, 0.f, 0.f, 0.f};
; #pragma unroll
;                 for (int ks = 0; ks < 4; ++ks) {
;                     const LAS unsigned char* ap = bb + SB_QD + (32 * ks + 4 * g + qq) * HP + (16 * I + 4 * pp) * 2;
;                     o = __builtin_amdgcn_mfma_f32_16x16x32_bf16(sb[ks], cat8(lds_tr(ap), lds_tr(ap + 16 * HP)), o, 0, 0, 0);
;                 }
; #pragma unroll
;                 for (int sp = 0; sp < 2; ++sp) {
;                     if (2 * sp > I) break;
;                     const LAS unsigned char* pr = bb + SB_P + (16 * I + li) * PP + (32 * sp + 4 * g) * 2;
;                     const u32x2 lo = *(const LAS u32x2*)pr; u32x2 hi = (u32x2){0u, 0u};
;                     if (2 * sp + 1 <= I) hi = *(const LAS u32x2*)(pr + 32);
;                     o = __builtin_amdgcn_mfma_f32_16x16x32_bf16(vf[sp], cat8u(lo, hi), o, 0, 0, 0);
;                 }
;                 { u32x2 w; w.x = pk2(o.x, o.y); w.y = pk2(o.z, o.w); *(u32x2*)(orow + (long)(16 * I + li) * ost) = w; }
;             }
.LBB0_408:
	ds_read_b64_tr_b16 v[100:101], v157 offset:50688
	ds_read_b64_tr_b16 v[102:103], v157 offset:55296
	ds_read_b64_tr_b16 v[96:97], v157 offset:59904
	ds_read_b64_tr_b16 v[98:99], v157 offset:64512
	s_add_i32 s23, s30, 2
	s_cmp_lt_u32 s23, 4
	s_cbranch_scc1 .LBB0_412
	v_cvt_pk_bf16_f32 v104, v76, v77
	v_cvt_pk_bf16_f32 v105, v78, v79
	v_cvt_pk_bf16_f32 v106, v92, v93
	v_cvt_pk_bf16_f32 v107, v94, v95
	v_add_u32_e32 v165, v139, v141
	v_cvt_pk_bf16_f32 v108, v80, v81
	v_cvt_pk_bf16_f32 v109, v82, v83
	v_cvt_pk_bf16_f32 v110, v88, v89
	v_cvt_pk_bf16_f32 v111, v90, v91
	ds_read_b64_tr_b16 v[176:177], v165 offset:2560
	ds_read_b64_tr_b16 v[174:175], v165
	ds_read_b64_tr_b16 v[178:179], v165 offset:32
	ds_read_b64_tr_b16 v[182:183], v165 offset:64
	ds_read_b64_tr_b16 v[186:187], v165 offset:96
	ds_read_b64_tr_b16 v[180:181], v165 offset:2592
	ds_read_b64_tr_b16 v[184:185], v165 offset:2624
	ds_read_b64_tr_b16 v[188:189], v165 offset:2656
	s_waitcnt lgkmcnt(6)
	v_mfma_f32_16x16x32_bf16 v[174:177], v[104:107], v[174:177], 0
	v_cvt_pk_bf16_f32 v166, v72, v73
	v_cvt_pk_bf16_f32 v167, v74, v75
	v_cvt_pk_bf16_f32 v168, v84, v85
	s_waitcnt lgkmcnt(2)
	v_mfma_f32_16x16x32_bf16 v[178:181], v[104:107], v[178:181], 0
	v_cvt_pk_bf16_f32 v169, v86, v87
	ds_read_b64_tr_b16 v[192:193], v165 offset:7680
	ds_read_b64_tr_b16 v[190:191], v165 offset:5120
	ds_read_b64_tr_b16 v[194:195], v165 offset:5152
	ds_read_b64_tr_b16 v[198:199], v165 offset:5184
	ds_read_b64_tr_b16 v[202:203], v165 offset:5216
	ds_read_b64_tr_b16 v[196:197], v165 offset:7712
	ds_read_b64_tr_b16 v[200:201], v165 offset:7744
	ds_read_b64_tr_b16 v[204:205], v165 offset:7776
	v_cvt_pk_bf16_f32 v170, v64, v65
	s_waitcnt lgkmcnt(6)
	v_mfma_f32_16x16x32_bf16 v[174:177], v[108:111], v[190:193], v[174:177]
	ds_read_b64_tr_b16 v[192:193], v165 offset:12800
	ds_read_b64_tr_b16 v[190:191], v165 offset:10240
	ds_read_b64_tr_b16 v[206:207], v165 offset:10272
	ds_read_b64_tr_b16 v[210:211], v165 offset:10304
	ds_read_b64_tr_b16 v[214:215], v165 offset:10336
	ds_read_b64_tr_b16 v[208:209], v165 offset:12832
	ds_read_b64_tr_b16 v[212:213], v165 offset:12864
	ds_read_b64_tr_b16 v[216:217], v165 offset:12896
	v_cvt_pk_bf16_f32 v171, v66, v67
	v_cvt_pk_bf16_f32 v172, v68, v69
	s_waitcnt lgkmcnt(10)
	v_mfma_f32_16x16x32_bf16 v[178:181], v[108:111], v[194:197], v[178:181]
	v_cvt_pk_bf16_f32 v173, v70, v71
	v_add_u32_e32 v234, v140, v142
	v_mov_b32_e32 v220, v115
	v_mfma_f32_16x16x32_bf16 v[182:185], v[104:107], v[182:185], 0
	v_mov_b32_e32 v221, v115
	s_and_b64 s[18:19], s[6:7], exec
	s_cselect_b32 s12, s22, s20
	s_waitcnt lgkmcnt(6)
	v_mfma_f32_16x16x32_bf16 v[174:177], v[166:169], v[190:193], v[174:177]
	ds_read_b64_tr_b16 v[192:193], v165 offset:17920
	ds_read_b64 v[218:219], v234 offset:40960
	ds_read_b64_tr_b16 v[190:191], v165 offset:15360
	ds_read_b64_tr_b16 v[222:223], v165 offset:15392
	ds_read_b64_tr_b16 v[226:227], v165 offset:15424
	ds_read_b64_tr_b16 v[230:231], v165 offset:15456
	ds_read_b64_tr_b16 v[224:225], v165 offset:17952
	ds_read_b64_tr_b16 v[228:229], v165 offset:17984
	ds_read_b64_tr_b16 v[232:233], v165 offset:18016
	v_add_u32_e32 v165, 0xa800, v234
	s_waitcnt lgkmcnt(11)
	v_mfma_f32_16x16x32_bf16 v[178:181], v[166:169], v[206:209], v[178:181]
	s_lshl_b64 s[18:19], s[12:13], 11
	v_mfma_f32_16x16x32_bf16 v[182:185], v[108:111], v[198:201], v[182:185]
	s_waitcnt lgkmcnt(6)
	v_mfma_f32_16x16x32_bf16 v[174:177], v[170:173], v[190:193], v[174:177]
	ds_read2_b64 v[192:195], v165 offset0:32 offset1:36
	v_add_u32_e32 v165, 0xb000, v234
	ds_read_b64 v[190:191], v234 offset:45632
	s_waitcnt lgkmcnt(4)
	v_mfma_f32_16x16x32_bf16 v[178:181], v[170:173], v[222:225], v[178:181]
	v_mfma_f32_16x16x32_bf16 v[182:185], v[166:169], v[210:213], v[182:185]
	v_mfma_f32_16x16x32_bf16 v[104:107], v[104:107], v[186:189], 0
	s_waitcnt lgkmcnt(1)
	v_mfma_f32_16x16x32_bf16 v[178:181], v[100:103], v[192:195], v[178:181]
	ds_read2_b64 v[192:195], v165 offset0:64 offset1:68
	v_add_u32_e32 v165, 0xb800, v234
	v_mfma_f32_16x16x32_bf16 v[182:185], v[170:173], v[226:229], v[182:185]
	v_mfma_f32_16x16x32_bf16 v[104:107], v[108:111], v[202:205], v[104:107]
	ds_read2_b64 v[108:111], v165 offset0:96 offset1:100
	s_waitcnt lgkmcnt(1)
	v_mfma_f32_16x16x32_bf16 v[182:185], v[100:103], v[192:195], v[182:185]
	v_mov_b32_e32 v192, v115
	v_mov_b32_e32 v193, v115
	v_mfma_f32_16x16x32_bf16 v[104:107], v[166:169], v[214:217], v[104:107]
	v_mfma_f32_16x16x32_bf16 v[174:177], v[100:103], v[218:221], v[174:177]
	v_mfma_f32_16x16x32_bf16 v[182:185], v[96:99], v[190:193], v[182:185]
	v_lshl_add_u64 v[190:191], v[118:119], 0, s[18:19]
	s_nop 5
	v_cvt_pk_bf16_f32 v174, v174, v175
	v_cvt_pk_bf16_f32 v175, v176, v177
	v_mfma_f32_16x16x32_bf16 v[104:107], v[170:173], v[230:233], v[104:107]
	v_lshl_add_u64 v[176:177], v[120:121], 1, v[190:191]
	global_store_dwordx2 v[176:177], v[174:175], off
	v_cvt_pk_bf16_f32 v174, v178, v179
	v_cvt_pk_bf16_f32 v175, v180, v181
	v_lshl_add_u64 v[166:167], v[122:123], 1, v[190:191]
	global_store_dwordx2 v[166:167], v[174:175], off
	ds_read2_b64 v[166:169], v165 offset0:104 offset1:108
	s_waitcnt lgkmcnt(1)
	v_mfma_f32_16x16x32_bf16 v[104:107], v[100:103], v[108:111], v[104:107]
	v_cvt_pk_bf16_f32 v170, v182, v183
	v_cvt_pk_bf16_f32 v171, v184, v185
	v_lshl_add_u64 v[108:109], v[124:125], 1, v[190:191]
	s_waitcnt lgkmcnt(0)
	v_mfma_f32_16x16x32_bf16 v[104:107], v[96:99], v[166:169], v[104:107]
	global_store_dwordx2 v[108:109], v[170:171], off
	s_nop 6
	v_cvt_pk_bf16_f32 v104, v104, v105
	v_cvt_pk_bf16_f32 v105, v106, v107
	v_lshl_add_u64 v[106:107], v[126:127], 1, v[190:191]
	global_store_dwordx2 v[106:107], v[104:105], off

; #define LAS __attribute__((address_space(3)))
; __device__ __forceinline__ unsigned pk2(float lo, float hi) { const f32x2_t v = {lo, hi}; const bf16x2_t b = __builtin_convertvector(v, bf16x2_t); return __builtin_bit_cast(unsigned, b); }
; __device__ __forceinline__ bf16x8 cat8(const s16x4 a, const s16x4 b) { return __builtin_shufflevector(a, b, 0, 1, 2, 3, 4, 5, 6, 7); }
; __device__ __forceinline__ void hgrn_scan(const Params& p, LAS unsigned char* lds, int chain) {
;     ...
;         bf16x8 vf[2];
; #pragma unroll
;         for (int sp = 0; sp < 2; ++sp) {
;             const LAS unsigned char* vb0 = bb + SB_V + (32 * sp + 4 * g + qq) * VP + (16 * wave + 4 * pp) * 2;
;             vf[sp] = cat8(lds_tr(vb0), lds_tr(vb0 + 16 * VP));
;         }
;         if (lat) {
;             bf16x8 sb[4];
; #pragma unroll
;             for (int ks = 0; ks < 4; ++ks) sb[ks] = pack_p(S[2 * ks], S[2 * ks + 1]);
;             bf16* orow = O + (long)hg_row(dir, b, 64 * c) * WA;
; #pragma unroll
;             for (int I = 0; I < 4; ++I) {
;                 f32x4 o = (f32x4){0.f, 0.f, 0.f, 0.f};
; #pragma unroll
;                 for (int ks = 0; ks < 4; ++ks) {
;                     const LAS unsigned char* ap = bb + SB_QD + (32 * ks + 4 * g + qq) * HP + (16 * I + 4 * pp) * 2;
;                     o = __builtin_amdgcn_mfma_f32_16x16x32_bf16(sb[ks], cat8(lds_tr(ap), lds_tr(ap + 16 * HP)), o, 0, 0, 0);
;                 }
; #pragma unroll
;                 for (int sp = 0; sp < 2; ++sp) {
;                     if (2 * sp > I) break;
;                     const LAS unsigned char* pr = bb + SB_P + (16 * I + li) * PP + (32 * sp + 4 * g) * 2;
;                     const u32x2 lo = *(const LAS u32x2*)pr; u32x2 hi = (u32x2){0u, 0u};
;                     if (2 * sp + 1 <= I) hi = *(const LAS u32x2*)(pr + 32);
;                     o = __builtin_amdgcn_mfma_f32_16x16x32_bf16(vf[sp], cat8u(lo, hi), o, 0, 0, 0);
;                 }
;                 { u32x2 w; w.x = pk2(o.x, o.y); w.y = pk2(o.z, o.w); *(u32x2*)(orow + (long)(16 * I + li) * ost) = w; }
;             }
.LBB0_422:
	s_waitcnt lgkmcnt(0)
	s_barrier
	ds_read_b64_tr_b16 v[100:101], v161
	ds_read_b64_tr_b16 v[102:103], v161 offset:4608
	ds_read_b64_tr_b16 v[96:97], v161 offset:9216
	ds_read_b64_tr_b16 v[98:99], v161 offset:13824
	s_cmp_lt_u32 s23, 4
	s_cbranch_scc1 .LBB0_426
	v_cvt_pk_bf16_f32 v104, v76, v77
	v_cvt_pk_bf16_f32 v105, v78, v79
	v_cvt_pk_bf16_f32 v106, v92, v93
	v_cvt_pk_bf16_f32 v107, v94, v95
	ds_read_b64_tr_b16 v[176:177], v162 offset:2560
	ds_read_b64_tr_b16 v[174:175], v162
	ds_read_b64_tr_b16 v[178:179], v162 offset:32
	ds_read_b64_tr_b16 v[182:183], v162 offset:64
	ds_read_b64_tr_b16 v[186:187], v162 offset:96
	ds_read_b64_tr_b16 v[180:181], v162 offset:2592
	ds_read_b64_tr_b16 v[184:185], v162 offset:2624
	ds_read_b64_tr_b16 v[188:189], v162 offset:2656
	v_cvt_pk_bf16_f32 v108, v80, v81
	v_cvt_pk_bf16_f32 v109, v82, v83
	v_cvt_pk_bf16_f32 v110, v88, v89
	v_cvt_pk_bf16_f32 v111, v90, v91
	s_waitcnt lgkmcnt(6)
	v_mfma_f32_16x16x32_bf16 v[174:177], v[104:107], v[174:177], 0
	ds_read_b64_tr_b16 v[192:193], v162 offset:7680
	ds_read_b64_tr_b16 v[190:191], v162 offset:5120
	ds_read_b64_tr_b16 v[194:195], v162 offset:5152
	ds_read_b64_tr_b16 v[198:199], v162 offset:5184
	ds_read_b64_tr_b16 v[202:203], v162 offset:5216
	ds_read_b64_tr_b16 v[196:197], v162 offset:7712
	ds_read_b64_tr_b16 v[200:201], v162 offset:7744
	ds_read_b64_tr_b16 v[204:205], v162 offset:7776
	v_cvt_pk_bf16_f32 v166, v72, v73
	v_cvt_pk_bf16_f32 v167, v74, v75
	s_waitcnt lgkmcnt(10)
	v_mfma_f32_16x16x32_bf16 v[178:181], v[104:107], v[178:181], 0
	v_cvt_pk_bf16_f32 v168, v84, v85
	v_cvt_pk_bf16_f32 v169, v86, v87
	v_cvt_pk_bf16_f32 v170, v64, v65
	s_waitcnt lgkmcnt(6)
	v_mfma_f32_16x16x32_bf16 v[174:177], v[108:111], v[190:193], v[174:177]
	ds_read_b64_tr_b16 v[192:193], v162 offset:12800
	ds_read_b64_tr_b16 v[190:191], v162 offset:10240
	ds_read_b64_tr_b16 v[206:207], v162 offset:10272
	ds_read_b64_tr_b16 v[210:211], v162 offset:10304
	ds_read_b64_tr_b16 v[214:215], v162 offset:10336
	ds_read_b64_tr_b16 v[208:209], v162 offset:12832
	ds_read_b64_tr_b16 v[212:213], v162 offset:12864
	ds_read_b64_tr_b16 v[216:217], v162 offset:12896
	v_cvt_pk_bf16_f32 v171, v66, v67
	v_cvt_pk_bf16_f32 v172, v68, v69
	s_waitcnt lgkmcnt(10)
	v_mfma_f32_16x16x32_bf16 v[178:181], v[108:111], v[194:197], v[178:181]
	v_cvt_pk_bf16_f32 v173, v70, v71
	v_add_u32_e32 v165, 0x800, v163
	v_mov_b32_e32 v220, v115
	v_mfma_f32_16x16x32_bf16 v[182:185], v[104:107], v[182:185], 0
	v_mov_b32_e32 v221, v115
	s_add_i32 s12, s22, 64
	s_sub_i32 s18, s20, 64
	s_waitcnt lgkmcnt(6)
	v_mfma_f32_16x16x32_bf16 v[174:177], v[166:169], v[190:193], v[174:177]
	ds_read_b64_tr_b16 v[192:193], v162 offset:17920
	ds_read_b64 v[218:219], v163
	ds_read_b64_tr_b16 v[190:191], v162 offset:15360
	ds_read_b64_tr_b16 v[222:223], v162 offset:15392
	ds_read_b64_tr_b16 v[226:227], v162 offset:15424
	ds_read_b64_tr_b16 v[230:231], v162 offset:15456
	ds_read_b64_tr_b16 v[224:225], v162 offset:17952
	ds_read_b64_tr_b16 v[228:229], v162 offset:17984
	ds_read_b64_tr_b16 v[232:233], v162 offset:18016
	s_and_b64 s[16:17], s[6:7], exec
	s_cselect_b32 s12, s12, s18
	s_waitcnt lgkmcnt(11)
	v_mfma_f32_16x16x32_bf16 v[178:181], v[166:169], v[206:209], v[178:181]
	s_lshl_b64 s[16:17], s[12:13], 11
	v_mfma_f32_16x16x32_bf16 v[182:185], v[108:111], v[198:201], v[182:185]
	s_waitcnt lgkmcnt(6)
	v_mfma_f32_16x16x32_bf16 v[174:177], v[170:173], v[190:193], v[174:177]
	ds_read2_b64 v[192:195], v165 offset0:32 offset1:36
	v_add_u32_e32 v165, 0x1000, v163
	ds_read_b64 v[190:191], v163 offset:4672
	s_waitcnt lgkmcnt(4)
	v_mfma_f32_16x16x32_bf16 v[178:181], v[170:173], v[222:225], v[178:181]
	v_mfma_f32_16x16x32_bf16 v[182:185], v[166:169], v[210:213], v[182:185]
	v_mfma_f32_16x16x32_bf16 v[104:107], v[104:107], v[186:189], 0
	s_waitcnt lgkmcnt(1)
	v_mfma_f32_16x16x32_bf16 v[178:181], v[100:103], v[192:195], v[178:181]
	ds_read2_b64 v[192:195], v165 offset0:64 offset1:68
	v_add_u32_e32 v165, 0x1800, v163
	v_mfma_f32_16x16x32_bf16 v[182:185], v[170:173], v[226:229], v[182:185]
	v_mfma_f32_16x16x32_bf16 v[104:107], v[108:111], v[202:205], v[104:107]
	ds_read2_b64 v[108:111], v165 offset0:96 offset1:100
	s_waitcnt lgkmcnt(1)
	v_mfma_f32_16x16x32_bf16 v[182:185], v[100:103], v[192:195], v[182:185]
	v_mov_b32_e32 v192, v115
	v_mov_b32_e32 v193, v115
	v_mfma_f32_16x16x32_bf16 v[104:107], v[166:169], v[214:217], v[104:107]
	v_mfma_f32_16x16x32_bf16 v[174:177], v[100:103], v[218:221], v[174:177]
	v_mfma_f32_16x16x32_bf16 v[182:185], v[96:99], v[190:193], v[182:185]
	v_lshl_add_u64 v[190:191], v[118:119], 0, s[16:17]
	s_nop 5
	v_cvt_pk_bf16_f32 v174, v174, v175
	v_cvt_pk_bf16_f32 v175, v176, v177
	v_mfma_f32_16x16x32_bf16 v[104:107], v[170:173], v[230:233], v[104:107]
	v_lshl_add_u64 v[176:177], v[120:121], 1, v[190:191]
	global_store_dwordx2 v[176:177], v[174:175], off
	v_cvt_pk_bf16_f32 v174, v178, v179
	v_cvt_pk_bf16_f32 v175, v180, v181
	v_lshl_add_u64 v[166:167], v[122:123], 1, v[190:191]
	global_store_dwordx2 v[166:167], v[174:175], off
	ds_read2_b64 v[166:169], v165 offset0:104 offset1:108
	s_waitcnt lgkmcnt(1)
	v_mfma_f32_16x16x32_bf16 v[104:107], v[100:103], v[108:111], v[104:107]
	v_cvt_pk_bf16_f32 v170, v182, v183
	v_cvt_pk_bf16_f32 v171, v184, v185
	v_lshl_add_u64 v[108:109], v[124:125], 1, v[190:191]
	s_waitcnt lgkmcnt(0)
	v_mfma_f32_16x16x32_bf16 v[104:107], v[96:99], v[166:169], v[104:107]
	global_store_dwordx2 v[108:109], v[170:171], off
	s_nop 6
	v_cvt_pk_bf16_f32 v104, v104, v105
	v_cvt_pk_bf16_f32 v105, v106, v107
	v_lshl_add_u64 v[106:107], v[126:127], 1, v[190:191]
	global_store_dwordx2 v[106:107], v[104:105], off
